# MLA loop: s_setprio 1 under a real scalar condition (waves 4-7 only) instead of hipcc's exec-masked form that raised every wave
# speedup vs baseline: 1.0126x; 1.0126x over previous
; DI float bfs2f(short v) { return __uint_as_float(((unsigned)(u16)v) << 16); }
; DI u16 f2bf(float a) { return (u16)(pk2(a, 0.f) & 0xffffu); }
; #define MLA_GLOAD(T) do { rkn = *(const u32x4*)(kvsrc + (size_t)(T) * 64 * KVP); rvv = *(const u32x4*)(kvsrc + (size_t)(T) * 64 * KVP + 64); \
;     if (kr_on) rkr = *(const u32x4*)(krsrc + (size_t)(T) * 64 * 32); } while (0)
; #define MLA_LSTORE(B) do { u16* kd = Kl + (B) * 64 * KP; u16* vd = Vl + (B) * 64 * VP; *(u32x4*)(kd + kdst0) = rkn; *(u32x4*)(vd + vdst) = rvv; \
;     if (kr_on) *(u32x4*)(kd + kdst2) = rkr; } while (0)
; DI void mla_unit(const Params& p, char* lds, int seqbase, int S, int h, int qb) {
;     ...
;   const float C = 0.10206207261596577f * LOG2E;
; #pragma unroll
;   for (int j = 0; j < 8; ++j) {
;     const float c = ct[pos * 16 + 8 * hi + j], s = st[pos * 16 + 8 * hi + j];
;     const float t1 = bfs2f(qf[4][j]), t2 = bfs2f(qf[5][j]);
;     qf[4][j] = (short)f2bf((t1 * c - t2 * s) * C); qf[5][j] = (short)f2bf((t1 * s + t2 * c) * C);
;   }
; #pragma unroll
;   for (int d0 = 0; d0 < 4; ++d0)
; #pragma unroll
;     for (int j = 0; j < 8; ++j) qf[d0][j] = (short)f2bf(bfs2f(qf[d0][j]) * C);
;   const int srow = tid >> 3, sc = tid & 7, rrow = (tid >> 2) & 63, rc = tid & 3;
;   const bool kr_on = tid < 256;
;   const u16* kvsrc = KV + (size_t)(seqbase + srow) * KVP + h * 128 + sc * 8;
;   const u16* krsrc = KR + (size_t)(seqbase + rrow) * 32 + rc * 8;
;   const int kdst0 = srow * KP + sc * 8, kdst2 = rrow * KP + 64 + rc * 8, vdst = srow * VP + sc * 8;
;   float l_run = 0.f; f32x16 o0 = {}, o1 = {}, negm = {};
;   const int nkt = S >> 6;
;   u32x4 rkn, rkr, rvv;
;     ...
;   MLA_GLOAD(0); MLA_LSTORE(0);
;   MLA_GLOAD(1); MLA_LSTORE(1);
;   __syncthreads();
;   int cur = 0, nx2 = 2;
;   if (wid >= 4) __builtin_amdgcn_s_setprio(1);
.Lmd_svb5:
	s_waitcnt vmcnt(0)
	s_waitcnt lgkmcnt(0)
	s_barrier
	s_cmp_eq_u64 s[4:5], 0
	s_cbranch_scc1 .Lmla_noprio1
	s_setprio 1
.Lmla_noprio1:
	s_lshl_b32 s28, s48, 6
	s_and_b32 s28, s28, 0x800
	s_or_b32 s28, s28, s57
	v_lshlrev_b64 v[42:43], 6, v[50:51]
	v_mov_b32_e32 v0, s28
	v_lshl_add_u64 v[170:171], v[156:157], 0, v[42:43]
	v_mad_i64_i32 v[42:43], s[28:29], v56, s59, v[0:1]
	v_and_b32_e32 v45, 0xffff0000, v26
	v_lshlrev_b32_e32 v44, 16, v26
	v_lshl_add_u64 v[172:173], v[158:159], 0, v[42:43]
	v_and_b32_e32 v43, 0xffff0000, v30
	v_lshlrev_b32_e32 v42, 16, v30
	v_pk_mul_f32 v[46:47], v[34:35], v[44:45]
	v_lshlrev_b32_e32 v30, 16, v27
	v_pk_fma_f32 v[46:47], v[38:39], v[42:43], v[46:47]
	v_pk_mul_f32 v[38:39], v[38:39], v[44:45]
	v_pk_mul_f32 v[46:47], v[46:47], s[38:39] op_sel_hi:[1,0]
	v_pk_fma_f32 v[34:35], v[34:35], v[42:43], v[38:39] neg_lo:[0,0,1] neg_hi:[0,0,1]
	v_cvt_pk_bf16_f32 v108, v46, v47
	v_pk_mul_f32 v[34:35], v[34:35], s[38:39] op_sel_hi:[1,0]
	v_mov_b32_e32 v0, v1
	v_cvt_pk_bf16_f32 v112, v34, v35
	v_and_b32_e32 v35, 0xffff0000, v31
	v_lshlrev_b32_e32 v34, 16, v31
	v_and_b32_e32 v31, 0xffff0000, v27
	v_pk_mul_f32 v[26:27], v[40:41], v[34:35]
	v_ashrrev_i32_e32 v169, 31, v168
	v_pk_fma_f32 v[26:27], v[36:37], v[30:31], v[26:27]
	s_mov_b32 s36, 0
	v_pk_mul_f32 v[26:27], v[26:27], s[38:39] op_sel_hi:[1,0]
	s_mov_b32 s63, 2
	v_cvt_pk_bf16_f32 v109, v26, v27
	v_pk_mul_f32 v[26:27], v[40:41], v[30:31]
	v_and_b32_e32 v31, 0xffff0000, v28
	v_pk_fma_f32 v[26:27], v[36:37], v[34:35], v[26:27] neg_lo:[0,0,1] neg_hi:[0,0,1]
	v_lshlrev_b32_e32 v30, 16, v28
	v_pk_mul_f32 v[26:27], v[26:27], s[38:39] op_sel_hi:[1,0]
	v_mov_b32_e32 v153, 0
	v_cvt_pk_bf16_f32 v113, v26, v27
	v_and_b32_e32 v27, 0xffff0000, v32
	v_lshlrev_b32_e32 v26, 16, v32
	v_pk_mul_f32 v[34:35], v[22:23], v[26:27]
	v_pk_mul_f32 v[22:23], v[22:23], v[30:31]
	v_pk_fma_f32 v[34:35], v[18:19], v[30:31], v[34:35]
	v_pk_fma_f32 v[18:19], v[18:19], v[26:27], v[22:23] neg_lo:[0,0,1] neg_hi:[0,0,1]
	v_and_b32_e32 v23, 0xffff0000, v29
	v_pk_mul_f32 v[18:19], v[18:19], s[38:39] op_sel_hi:[1,0]
	v_lshlrev_b32_e32 v22, 16, v29
	v_cvt_pk_bf16_f32 v114, v18, v19
	v_and_b32_e32 v19, 0xffff0000, v33
	v_lshlrev_b32_e32 v18, 16, v33
	v_pk_mul_f32 v[26:27], v[24:25], v[18:19]
	v_pk_mul_f32 v[34:35], v[34:35], s[38:39] op_sel_hi:[1,0]
	v_pk_fma_f32 v[26:27], v[20:21], v[22:23], v[26:27]
	v_pk_mul_f32 v[22:23], v[24:25], v[22:23]
	v_pk_mul_f32 v[26:27], v[26:27], s[38:39] op_sel_hi:[1,0]
	v_pk_fma_f32 v[18:19], v[20:21], v[18:19], v[22:23] neg_lo:[0,0,1] neg_hi:[0,0,1]
	v_cvt_pk_bf16_f32 v110, v34, v35
	v_pk_mul_f32 v[18:19], v[18:19], s[38:39] op_sel_hi:[1,0]
	v_cvt_pk_bf16_f32 v111, v26, v27
	v_cvt_pk_bf16_f32 v115, v18, v19
	v_and_b32_e32 v19, 0xffff0000, v14
	v_lshlrev_b32_e32 v18, 16, v14
	v_pk_mul_f32 v[18:19], v[18:19], s[38:39] op_sel_hi:[1,0]
	s_mov_b64 s[46:47], 0
	v_cvt_pk_bf16_f32 v116, v18, v19
	v_and_b32_e32 v19, 0xffff0000, v15
	v_lshlrev_b32_e32 v18, 16, v15
	v_pk_mul_f32 v[14:15], v[18:19], s[38:39] op_sel_hi:[1,0]
	s_mov_b32 s64, 0
	v_cvt_pk_bf16_f32 v117, v14, v15
	v_and_b32_e32 v15, 0xffff0000, v16
	v_lshlrev_b32_e32 v14, 16, v16
	v_pk_mul_f32 v[14:15], v[14:15], s[38:39] op_sel_hi:[1,0]
	s_nop 0
	v_cvt_pk_bf16_f32 v118, v14, v15
	v_and_b32_e32 v15, 0xffff0000, v17
	v_lshlrev_b32_e32 v14, 16, v17
	v_pk_mul_f32 v[14:15], v[14:15], s[38:39] op_sel_hi:[1,0]
	s_nop 0
	v_cvt_pk_bf16_f32 v119, v14, v15
	v_and_b32_e32 v15, 0xffff0000, v10
	v_lshlrev_b32_e32 v14, 16, v10
	v_pk_mul_f32 v[14:15], v[14:15], s[38:39] op_sel_hi:[1,0]
	s_nop 0
	v_cvt_pk_bf16_f32 v120, v14, v15
	v_and_b32_e32 v15, 0xffff0000, v11
	v_lshlrev_b32_e32 v14, 16, v11
	v_pk_mul_f32 v[10:11], v[14:15], s[38:39] op_sel_hi:[1,0]
	v_mov_b32_e32 v14, v1
	v_cvt_pk_bf16_f32 v121, v10, v11
	v_and_b32_e32 v11, 0xffff0000, v12
	v_lshlrev_b32_e32 v10, 16, v12
	v_pk_mul_f32 v[10:11], v[10:11], s[38:39] op_sel_hi:[1,0]
	v_mov_b32_e32 v15, v1
	v_cvt_pk_bf16_f32 v122, v10, v11
	v_and_b32_e32 v11, 0xffff0000, v13
	v_lshlrev_b32_e32 v10, 16, v13
	v_pk_mul_f32 v[10:11], v[10:11], s[38:39] op_sel_hi:[1,0]
	v_mov_b32_e32 v12, v1
	v_cvt_pk_bf16_f32 v123, v10, v11
	v_and_b32_e32 v11, 0xffff0000, v6
	v_lshlrev_b32_e32 v10, 16, v6
	v_pk_mul_f32 v[10:11], v[10:11], s[38:39] op_sel_hi:[1,0]
	v_mov_b32_e32 v13, v1
	v_cvt_pk_bf16_f32 v124, v10, v11
	v_and_b32_e32 v11, 0xffff0000, v7
	v_lshlrev_b32_e32 v10, 16, v7
	v_pk_mul_f32 v[6:7], v[10:11], s[38:39] op_sel_hi:[1,0]
	v_mov_b32_e32 v10, v1
	v_cvt_pk_bf16_f32 v125, v6, v7
	v_and_b32_e32 v7, 0xffff0000, v8
	v_lshlrev_b32_e32 v6, 16, v8
	v_pk_mul_f32 v[6:7], v[6:7], s[38:39] op_sel_hi:[1,0]
	v_mov_b32_e32 v8, v1
	v_cvt_pk_bf16_f32 v126, v6, v7
	v_and_b32_e32 v7, 0xffff0000, v9
	v_lshlrev_b32_e32 v6, 16, v9
	v_pk_mul_f32 v[6:7], v[6:7], s[38:39] op_sel_hi:[1,0]
	v_mov_b32_e32 v9, v1
	v_cvt_pk_bf16_f32 v127, v6, v7
	v_and_b32_e32 v7, 0xffff0000, v2
	v_lshlrev_b32_e32 v6, 16, v2
	v_pk_mul_f32 v[6:7], v[6:7], s[38:39] op_sel_hi:[1,0]
	v_mov_b32_e32 v11, v1
	v_cvt_pk_bf16_f32 v128, v6, v7
	v_and_b32_e32 v7, 0xffff0000, v3
	v_lshlrev_b32_e32 v6, 16, v3
	v_pk_mul_f32 v[2:3], v[6:7], s[38:39] op_sel_hi:[1,0]
	v_mov_b32_e32 v6, v1
	v_cvt_pk_bf16_f32 v129, v2, v3
	v_and_b32_e32 v3, 0xffff0000, v4
	v_lshlrev_b32_e32 v2, 16, v4
	v_pk_mul_f32 v[2:3], v[2:3], s[38:39] op_sel_hi:[1,0]
	v_mov_b32_e32 v4, v1
	v_cvt_pk_bf16_f32 v130, v2, v3
	v_and_b32_e32 v3, 0xffff0000, v5
	v_lshlrev_b32_e32 v2, 16, v5
	v_pk_mul_f32 v[2:3], v[2:3], s[38:39] op_sel_hi:[1,0]
	v_mov_b32_e32 v5, v1
	v_cvt_pk_bf16_f32 v131, v2, v3
	v_mov_b32_e32 v2, v1
	v_mov_b32_e32 v3, v1
	v_mov_b32_e32 v7, v1
	v_mov_b64_e32 v[46:47], v[14:15]
	v_mov_b64_e32 v[30:31], v[14:15]
	v_mov_b64_e32 v[62:63], v[14:15]
	v_mov_b64_e32 v[44:45], v[12:13]
	v_mov_b64_e32 v[42:43], v[10:11]
	v_mov_b64_e32 v[40:41], v[8:9]
	v_mov_b64_e32 v[38:39], v[6:7]
	v_mov_b64_e32 v[36:37], v[4:5]
	v_mov_b64_e32 v[34:35], v[2:3]
	v_mov_b64_e32 v[32:33], v[0:1]
	v_mov_b64_e32 v[28:29], v[12:13]
	v_mov_b64_e32 v[26:27], v[10:11]
	v_mov_b64_e32 v[24:25], v[8:9]
	v_mov_b64_e32 v[22:23], v[6:7]
	v_mov_b64_e32 v[20:21], v[4:5]
	v_mov_b64_e32 v[18:19], v[2:3]
	v_mov_b64_e32 v[16:17], v[0:1]
	v_mov_b64_e32 v[60:61], v[12:13]
	v_mov_b64_e32 v[58:59], v[10:11]
	v_mov_b64_e32 v[56:57], v[8:9]
	v_mov_b64_e32 v[54:55], v[6:7]
	v_mov_b64_e32 v[52:53], v[4:5]
	v_mov_b64_e32 v[50:51], v[2:3]
	v_mov_b64_e32 v[48:49], v[0:1]
	s_branch .LBB0_1077

; DI float bfs2f(short v) { return __uint_as_float(((unsigned)(u16)v) << 16); }
; DI u16 f2bf(float a) { return (u16)(pk2(a, 0.f) & 0xffffu); }
; #define MLA_GLOAD(T) do { rkn = *(const u32x4*)(kvsrc + (size_t)(T) * 64 * KVP); rvv = *(const u32x4*)(kvsrc + (size_t)(T) * 64 * KVP + 64); \
;     if (kr_on) rkr = *(const u32x4*)(krsrc + (size_t)(T) * 64 * 32); } while (0)
; #define MLA_LSTORE(B) do { u16* kd = Kl + (B) * 64 * KP; u16* vd = Vl + (B) * 64 * VP; *(u32x4*)(kd + kdst0) = rkn; *(u32x4*)(vd + vdst) = rvv; \
;     if (kr_on) *(u32x4*)(kd + kdst2) = rkr; } while (0)
; DI void mla_unit(const Params& p, char* lds, int seqbase, int S, int h, int qb) {
;     ...
;   const float C = 0.10206207261596577f * LOG2E;
; #pragma unroll
;   for (int j = 0; j < 8; ++j) {
;     const float c = ct[pos * 16 + 8 * hi + j], s = st[pos * 16 + 8 * hi + j];
;     const float t1 = bfs2f(qf[4][j]), t2 = bfs2f(qf[5][j]);
;     qf[4][j] = (short)f2bf((t1 * c - t2 * s) * C); qf[5][j] = (short)f2bf((t1 * s + t2 * c) * C);
;   }
; #pragma unroll
;   for (int d0 = 0; d0 < 4; ++d0)
; #pragma unroll
;     for (int j = 0; j < 8; ++j) qf[d0][j] = (short)f2bf(bfs2f(qf[d0][j]) * C);
;   const int srow = tid >> 3, sc = tid & 7, rrow = (tid >> 2) & 63, rc = tid & 3;
;   const bool kr_on = tid < 256;
;   const u16* kvsrc = KV + (size_t)(seqbase + srow) * KVP + h * 128 + sc * 8;
;   const u16* krsrc = KR + (size_t)(seqbase + rrow) * 32 + rc * 8;
;   const int kdst0 = srow * KP + sc * 8, kdst2 = rrow * KP + 64 + rc * 8, vdst = srow * VP + sc * 8;
;   float l_run = 0.f; f32x16 o0 = {}, o1 = {}, negm = {};
;   const int nkt = S >> 6;
;   u32x4 rkn, rkr, rvv;
;     ...
;   MLA_GLOAD(0); MLA_LSTORE(0);
;   MLA_GLOAD(1); MLA_LSTORE(1);
;   __syncthreads();
;   int cur = 0, nx2 = 2;
;   if (wid >= 4) __builtin_amdgcn_s_setprio(1);
.Lmla_noprio0:
	v_add_u32_e32 v44, s41, v186
	s_and_b32 s18, s40, 0x800
	v_ashrrev_i32_e32 v45, 31, v44
	s_or_b32 s18, s18, s57
	v_lshlrev_b64 v[44:45], 6, v[44:45]
	v_add_u32_e32 v1, s41, v187
	v_mov_b32_e32 v2, s18
	v_lshl_add_u64 v[170:171], v[156:157], 0, v[44:45]
	v_mad_i64_i32 v[44:45], s[28:29], v1, s54, v[2:3]
	v_and_b32_e32 v47, 0xffff0000, v28
	v_lshlrev_b32_e32 v46, 16, v28
	v_lshl_add_u64 v[172:173], v[158:159], 0, v[44:45]
	v_and_b32_e32 v45, 0xffff0000, v32
	v_lshlrev_b32_e32 v44, 16, v32
	v_pk_mul_f32 v[48:49], v[36:37], v[46:47]
	v_lshlrev_b32_e32 v32, 16, v29
	v_pk_fma_f32 v[48:49], v[40:41], v[44:45], v[48:49]
	v_pk_mul_f32 v[40:41], v[40:41], v[46:47]
	v_pk_mul_f32 v[48:49], v[48:49], s[20:21] op_sel_hi:[1,0]
	v_pk_fma_f32 v[36:37], v[36:37], v[44:45], v[40:41] neg_lo:[0,0,1] neg_hi:[0,0,1]
	v_cvt_pk_bf16_f32 v110, v48, v49
	v_pk_mul_f32 v[36:37], v[36:37], s[20:21] op_sel_hi:[1,0]
	v_mov_b32_e32 v2, v3
	v_cvt_pk_bf16_f32 v114, v36, v37
	v_and_b32_e32 v37, 0xffff0000, v33
	v_lshlrev_b32_e32 v36, 16, v33
	v_and_b32_e32 v33, 0xffff0000, v29
	v_pk_mul_f32 v[28:29], v[42:43], v[36:37]
	v_ashrrev_i32_e32 v169, 31, v168
	v_pk_fma_f32 v[28:29], v[38:39], v[32:33], v[28:29]
	s_mov_b32 s18, 0
	v_pk_mul_f32 v[28:29], v[28:29], s[20:21] op_sel_hi:[1,0]
	s_mov_b32 s58, 2
	v_cvt_pk_bf16_f32 v111, v28, v29
	v_pk_mul_f32 v[28:29], v[42:43], v[32:33]
	v_and_b32_e32 v33, 0xffff0000, v30
	v_pk_fma_f32 v[28:29], v[38:39], v[36:37], v[28:29] neg_lo:[0,0,1] neg_hi:[0,0,1]
	v_lshlrev_b32_e32 v32, 16, v30
	v_pk_mul_f32 v[28:29], v[28:29], s[20:21] op_sel_hi:[1,0]
	v_mov_b32_e32 v1, 0
	v_cvt_pk_bf16_f32 v115, v28, v29
	v_and_b32_e32 v29, 0xffff0000, v34
	v_lshlrev_b32_e32 v28, 16, v34
	v_pk_mul_f32 v[36:37], v[24:25], v[28:29]
	v_pk_mul_f32 v[24:25], v[24:25], v[32:33]
	v_pk_fma_f32 v[36:37], v[20:21], v[32:33], v[36:37]
	v_pk_fma_f32 v[20:21], v[20:21], v[28:29], v[24:25] neg_lo:[0,0,1] neg_hi:[0,0,1]
	v_and_b32_e32 v25, 0xffff0000, v31
	v_pk_mul_f32 v[20:21], v[20:21], s[20:21] op_sel_hi:[1,0]
	v_lshlrev_b32_e32 v24, 16, v31
	v_cvt_pk_bf16_f32 v116, v20, v21
	v_and_b32_e32 v21, 0xffff0000, v35
	v_lshlrev_b32_e32 v20, 16, v35
	v_pk_mul_f32 v[28:29], v[26:27], v[20:21]
	v_pk_mul_f32 v[36:37], v[36:37], s[20:21] op_sel_hi:[1,0]
	v_pk_fma_f32 v[28:29], v[22:23], v[24:25], v[28:29]
	v_pk_mul_f32 v[24:25], v[26:27], v[24:25]
	v_pk_mul_f32 v[28:29], v[28:29], s[20:21] op_sel_hi:[1,0]
	v_pk_fma_f32 v[20:21], v[22:23], v[20:21], v[24:25] neg_lo:[0,0,1] neg_hi:[0,0,1]
	v_cvt_pk_bf16_f32 v112, v36, v37
	v_pk_mul_f32 v[20:21], v[20:21], s[20:21] op_sel_hi:[1,0]
	v_cvt_pk_bf16_f32 v113, v28, v29
	v_cvt_pk_bf16_f32 v117, v20, v21
	v_and_b32_e32 v21, 0xffff0000, v16
	v_lshlrev_b32_e32 v20, 16, v16
	v_pk_mul_f32 v[20:21], v[20:21], s[20:21] op_sel_hi:[1,0]
	s_mov_b64 s[38:39], 0
	v_cvt_pk_bf16_f32 v118, v20, v21
	v_and_b32_e32 v21, 0xffff0000, v17
	v_lshlrev_b32_e32 v20, 16, v17
	v_pk_mul_f32 v[16:17], v[20:21], s[20:21] op_sel_hi:[1,0]
	s_mov_b32 s59, 0
	v_cvt_pk_bf16_f32 v119, v16, v17
	v_and_b32_e32 v17, 0xffff0000, v18
	v_lshlrev_b32_e32 v16, 16, v18
	v_pk_mul_f32 v[16:17], v[16:17], s[20:21] op_sel_hi:[1,0]
	s_nop 0
	v_cvt_pk_bf16_f32 v120, v16, v17
	v_and_b32_e32 v17, 0xffff0000, v19
	v_lshlrev_b32_e32 v16, 16, v19
	v_pk_mul_f32 v[16:17], v[16:17], s[20:21] op_sel_hi:[1,0]
	s_nop 0
	v_cvt_pk_bf16_f32 v121, v16, v17
	v_and_b32_e32 v17, 0xffff0000, v12
	v_lshlrev_b32_e32 v16, 16, v12
	v_pk_mul_f32 v[16:17], v[16:17], s[20:21] op_sel_hi:[1,0]
	s_nop 0
	v_cvt_pk_bf16_f32 v122, v16, v17
	v_and_b32_e32 v17, 0xffff0000, v13
	v_lshlrev_b32_e32 v16, 16, v13
	v_pk_mul_f32 v[12:13], v[16:17], s[20:21] op_sel_hi:[1,0]
	v_mov_b32_e32 v16, v3
	v_cvt_pk_bf16_f32 v123, v12, v13
	v_and_b32_e32 v13, 0xffff0000, v14
	v_lshlrev_b32_e32 v12, 16, v14
	v_pk_mul_f32 v[12:13], v[12:13], s[20:21] op_sel_hi:[1,0]
	v_mov_b32_e32 v17, v3
	v_cvt_pk_bf16_f32 v124, v12, v13
	v_and_b32_e32 v13, 0xffff0000, v15
	v_lshlrev_b32_e32 v12, 16, v15
	v_pk_mul_f32 v[12:13], v[12:13], s[20:21] op_sel_hi:[1,0]
	v_mov_b32_e32 v14, v3
	v_cvt_pk_bf16_f32 v125, v12, v13
	v_and_b32_e32 v13, 0xffff0000, v8
	v_lshlrev_b32_e32 v12, 16, v8
	v_pk_mul_f32 v[12:13], v[12:13], s[20:21] op_sel_hi:[1,0]
	v_mov_b32_e32 v15, v3
	v_cvt_pk_bf16_f32 v126, v12, v13
	v_and_b32_e32 v13, 0xffff0000, v9
	v_lshlrev_b32_e32 v12, 16, v9
	v_pk_mul_f32 v[8:9], v[12:13], s[20:21] op_sel_hi:[1,0]
	v_mov_b32_e32 v12, v3
	v_cvt_pk_bf16_f32 v127, v8, v9
	v_and_b32_e32 v9, 0xffff0000, v10
	v_lshlrev_b32_e32 v8, 16, v10
	v_pk_mul_f32 v[8:9], v[8:9], s[20:21] op_sel_hi:[1,0]
	v_mov_b32_e32 v10, v3
	v_cvt_pk_bf16_f32 v128, v8, v9
	v_and_b32_e32 v9, 0xffff0000, v11
	v_lshlrev_b32_e32 v8, 16, v11
	v_pk_mul_f32 v[8:9], v[8:9], s[20:21] op_sel_hi:[1,0]
	v_mov_b32_e32 v11, v3
	v_cvt_pk_bf16_f32 v129, v8, v9
	v_and_b32_e32 v9, 0xffff0000, v4
	v_lshlrev_b32_e32 v8, 16, v4
	v_pk_mul_f32 v[8:9], v[8:9], s[20:21] op_sel_hi:[1,0]
	v_mov_b32_e32 v13, v3
	v_cvt_pk_bf16_f32 v130, v8, v9
	v_and_b32_e32 v9, 0xffff0000, v5
	v_lshlrev_b32_e32 v8, 16, v5
	v_pk_mul_f32 v[4:5], v[8:9], s[20:21] op_sel_hi:[1,0]
	v_mov_b32_e32 v8, v3
	v_cvt_pk_bf16_f32 v131, v4, v5
	v_and_b32_e32 v5, 0xffff0000, v6
	v_lshlrev_b32_e32 v4, 16, v6
	v_pk_mul_f32 v[4:5], v[4:5], s[20:21] op_sel_hi:[1,0]
	v_mov_b32_e32 v6, v3
	v_cvt_pk_bf16_f32 v132, v4, v5
	v_and_b32_e32 v5, 0xffff0000, v7
	v_lshlrev_b32_e32 v4, 16, v7
	v_pk_mul_f32 v[4:5], v[4:5], s[20:21] op_sel_hi:[1,0]
	v_mov_b32_e32 v7, v3
	v_cvt_pk_bf16_f32 v133, v4, v5
	v_mov_b32_e32 v4, v3
	v_mov_b32_e32 v5, v3
	v_mov_b32_e32 v9, v3
	v_mov_b64_e32 v[48:49], v[16:17]
	v_mov_b64_e32 v[32:33], v[16:17]
	v_mov_b64_e32 v[64:65], v[16:17]
	v_mov_b64_e32 v[46:47], v[14:15]
	v_mov_b64_e32 v[44:45], v[12:13]
	v_mov_b64_e32 v[42:43], v[10:11]
	v_mov_b64_e32 v[40:41], v[8:9]
	v_mov_b64_e32 v[38:39], v[6:7]
	v_mov_b64_e32 v[36:37], v[4:5]
	v_mov_b64_e32 v[34:35], v[2:3]
	v_mov_b64_e32 v[30:31], v[14:15]
	v_mov_b64_e32 v[28:29], v[12:13]
	v_mov_b64_e32 v[26:27], v[10:11]
	v_mov_b64_e32 v[24:25], v[8:9]
	v_mov_b64_e32 v[22:23], v[6:7]
	v_mov_b64_e32 v[20:21], v[4:5]
	v_mov_b64_e32 v[18:19], v[2:3]
	v_mov_b64_e32 v[62:63], v[14:15]
	v_mov_b64_e32 v[60:61], v[12:13]
	v_mov_b64_e32 v[58:59], v[10:11]
	v_mov_b64_e32 v[56:57], v[8:9]
	v_mov_b64_e32 v[54:55], v[6:7]
	v_mov_b64_e32 v[52:53], v[4:5]
	v_mov_b64_e32 v[50:51], v[2:3]
	s_branch .LBB0_1107
